# k19
# baseline (speedup 1.0000x reference)
; #define BAR __builtin_amdgcn_s_barrier()
; template <int EPI>
; __device__ __forceinline__ void gemm_phase(const GemmDesc d, u16* shm, unsigned sx, unsigned srank, unsigned snloc) {
;     ...
;       if (wr == 0) BAR;
;       int t2 = threadIdx.x; asm volatile("" : "+v"(t2));
;       const int wid2 = t2 >> 6, lane2 = t2 & 63, wr2 = wid2 >> 2, wc2 = wid2 & 3, fr2 = lane2 & 15, fq2 = lane2 >> 4;
;       float ssn = 0.f;
;       if constexpr (NEED_R) {
;         if (has_next && t2 < 256) ssn = SS_ROW(d.ss + (size_t)R_ROW(pmn, pnn, t2) * 16);
;       }
;       float* stg = (float*)((char*)shm + GEMM_LDS + 2048 + wid2 * 2304);
;       const float* lr = lds_r + (it & 1) * 256;
;       const int rl = lane2 >> 3, c4 = (lane2 & 7) * 4;
;       if constexpr (EPI == E_SWIGLU) {
;         using f32x2 = __attribute__((ext_vector_type(2))) float;
;         const int sw_row = lane2 >> 2, sw_c8 = (lane2 & 3) * 8;
;         u16* sw_base = d.outb + ((size_t)(brow >> 7) * 44 + pn * 2 + (wc2 >> 1)) * 8192
;                      + ((((sw_row * 64 + sw_c8 * 2) ^ ((sw_row >> 3) << 5)) + (wr2 * 8 + (wc2 & 1)) * 1024) >> 1);
; #pragma unroll
;         for (int ai = 0; ai < 2; ++ai)
; #pragma unroll
;           for (int m = 0; m < 4; ++m) {
;             const f32x4 r4 = *(const f32x4*)&lr[ai * 128 + wr2 * 64 + m * 16 + fq2 * 4];
;             const f32x4 rc4 = r4 * (-1.4426950408889634f), rr4 = r4 * r4;
; #pragma unroll
;             for (int n = 0; n < 2; ++n)
; #pragma unroll
;               for (int jp = 0; jp < 4; jp += 2) {
;                 const f32x2 a = {acc[ai][0][m][n][jp], acc[ai][0][m][n][jp + 1]}, b = {acc[ai][1][m][n][jp], acc[ai][1][m][n][jp + 1]};
;                 const f32x2 rc = {rc4[jp], rc4[jp + 1]}, rr = {rr4[jp], rr4[jp + 1]};
;                 const f32x2 tl = a * rc;
;                 f32x2 dd = {__builtin_amdgcn_exp2f(tl[0]), __builtin_amdgcn_exp2f(tl[1])};
;                 dd = dd + 1.0f;
;                 const f32x2 s = {__builtin_amdgcn_rcpf(dd[0]), __builtin_amdgcn_rcpf(dd[1])};
;                 const f32x2 o = (a * b) * (rr * s);
;                 stg[(fq2 * 4 + jp) * 36 + n * 16 + fr2] = o[0];
;                 stg[(fq2 * 4 + jp + 1) * 36 + n * 16 + fr2] = o[1];
;               }
;             {
;               const f32x4 v0 = *(const f32x4*)&stg[sw_row * 36 + sw_c8], v1 = *(const f32x4*)&stg[sw_row * 36 + sw_c8 + 4];
.LBB0_1450:
	v_mov_b32_e32 v139, v182
	v_mov_b32_e32 v140, 0x358637bd
	v_cmp_gt_i32_e32 vcc, s58, v139
	s_and_b64 s[34:35], s[26:27], vcc
	s_and_saveexec_b64 s[4:5], s[34:35]
	s_mov_b32 s31, 0x800000
	s_movk_i32 s28, 0x1000
	s_cbranch_execz .LBB0_1452
	v_lshl_add_u32 v128, s85, 8, v139
	v_ashrrev_i32_e32 v129, 31, v128
	v_lshlrev_b64 v[128:129], 6, v[128:129]
	v_lshl_add_u64 v[128:129], s[10:11], 0, v[128:129]
	global_load_dwordx4 v[140:143], v[128:129], off
	global_load_dwordx4 v[144:147], v[128:129], off offset:16
	global_load_dwordx4 v[148:151], v[128:129], off offset:32
	global_load_dwordx4 v[152:155], v[128:129], off offset:48
	s_waitcnt vmcnt(3)
	v_mov_b32_e32 v128, v140
	s_waitcnt vmcnt(2)
	v_mov_b32_e32 v129, v144
	v_mov_b32_e32 v144, v141
	v_mov_b32_e32 v140, v142
	v_mov_b32_e32 v141, v146
	v_mov_b32_e32 v146, v143
	s_waitcnt vmcnt(1)
	v_mov_b32_e32 v142, v148
	s_waitcnt vmcnt(0)
	v_mov_b32_e32 v143, v152
	v_mov_b32_e32 v152, v149
	v_pk_add_f32 v[128:129], v[128:129], v[144:145]
	v_mov_b32_e32 v148, v150
	v_mov_b32_e32 v149, v154
	v_pk_add_f32 v[142:143], v[142:143], v[152:153]
	v_pk_add_f32 v[128:129], v[140:141], v[128:129]
	v_mov_b32_e32 v154, v151
	v_pk_add_f32 v[140:141], v[148:149], v[142:143]
	v_pk_add_f32 v[128:129], v[146:147], v[128:129]
	v_pk_add_f32 v[140:141], v[154:155], v[140:141]
	v_add_f32_e32 v128, v128, v129
	v_add_f32_e32 v128, v128, v140
	v_add_f32_e32 v128, v128, v141
	v_fmamk_f32 v140, v128, 0x3a800000, v186
.LBB0_1452:
	s_or_b64 exec, exec, s[4:5]
	s_lshl_b32 s0, s70, 8
	s_and_b32 s18, s0, 0x100
	s_lshl_b32 s0, s18, 2
	s_add_i32 s0, s0, 0x20000
	v_add_u32_e32 v142, s0, v243
	s_mul_i32 s4, s89, 0x58
	s_lshl_b32 s5, s88, 1
	s_add_u32 s4, s4, s5
	s_mov_b32 s5, 0
	s_lshl_b64 s[4:5], s[4:5], 14
	s_add_u32 s4, s12, s4
	s_addc_u32 s5, s13, s5
	s_and_saveexec_b64 s[40:41], s[8:9]
	s_cbranch_execz .Lgu_realign_skip
	s_barrier
.Lgu_realign_skip:
	s_or_b64 exec, exec, s[40:41]
	ds_read_b128 v[150:153], v142
	ds_read_b128 v[158:161], v142 offset:20480
	ds_read_b128 v[154:157], v142 offset:64
	ds_read_b128 v[162:165], v142 offset:20544
	s_add_u32 s40, s4, 0x1000
	s_addc_u32 s41, s5, 0
	v_pk_mul_f32 v[120:121], v[124:125], v[120:121]
	v_pk_mul_f32 v[122:123], v[126:127], v[122:123]
	s_add_u32 s22, s4, 0xb0000
	s_addc_u32 s23, s5, 0
	v_pk_mul_f32 v[112:113], v[116:117], v[112:113]
	v_pk_mul_f32 v[114:115], v[118:119], v[114:115]
	s_add_u32 s96, s4, 0xb1000
	s_addc_u32 s97, s5, 0
	s_waitcnt lgkmcnt(2)
	v_pk_mul_f32 v[124:125], v[124:125], v[150:151]
	v_pk_mul_f32 v[126:127], v[126:127], v[152:153]
	v_pk_mul_f32 v[116:117], v[116:117], v[150:151]
	v_pk_mul_f32 v[118:119], v[118:119], v[152:153]
	v_exp_f32_e32 v124, v124
	v_exp_f32_e32 v125, v125
	v_exp_f32_e32 v126, v126
	v_exp_f32_e32 v127, v127
	v_exp_f32_e32 v116, v116
	v_exp_f32_e32 v117, v117
	v_exp_f32_e32 v118, v118
	v_exp_f32_e32 v119, v119
	v_pk_mul_f32 v[104:105], v[108:109], v[104:105]
	v_pk_mul_f32 v[106:107], v[110:111], v[106:107]
	v_pk_mul_f32 v[96:97], v[100:101], v[96:97]
	v_pk_mul_f32 v[98:99], v[102:103], v[98:99]
	v_pk_fma_f32 v[124:125], v[124:125], v[158:159], v[158:159]
	v_pk_fma_f32 v[126:127], v[126:127], v[160:161], v[160:161]
	v_pk_fma_f32 v[116:117], v[116:117], v[158:159], v[158:159]
	v_pk_fma_f32 v[118:119], v[118:119], v[160:161], v[160:161]
	v_rcp_f32_e32 v124, v124
	v_rcp_f32_e32 v125, v125
	v_rcp_f32_e32 v126, v126
	v_rcp_f32_e32 v127, v127
	v_rcp_f32_e32 v116, v116
	v_rcp_f32_e32 v117, v117
	v_rcp_f32_e32 v118, v118
	v_rcp_f32_e32 v119, v119
	v_pk_mul_f32 v[120:121], v[120:121], v[124:125]
	v_pk_mul_f32 v[122:123], v[122:123], v[126:127]
	v_pk_mul_f32 v[112:113], v[112:113], v[116:117]
	v_pk_mul_f32 v[114:115], v[114:115], v[118:119]
	ds_write2_b32 v242, v120, v112 offset1:16
	ds_write2_b32 v242, v121, v113 offset0:36 offset1:52
	ds_write2_b32 v242, v122, v114 offset0:72 offset1:88
	ds_write2_b32 v242, v123, v115 offset0:108 offset1:124
	ds_read_b128 v[166:169], v241
	ds_read_b128 v[170:173], v241 offset:16
	ds_read_b128 v[150:153], v142 offset:128
	ds_read_b128 v[158:161], v142 offset:20608
	s_waitcnt lgkmcnt(8)
	v_pk_mul_f32 v[108:109], v[108:109], v[154:155]
	v_pk_mul_f32 v[110:111], v[110:111], v[156:157]
	v_pk_mul_f32 v[100:101], v[100:101], v[154:155]
	v_pk_mul_f32 v[102:103], v[102:103], v[156:157]
	v_exp_f32_e32 v108, v108
	v_exp_f32_e32 v109, v109
	v_exp_f32_e32 v110, v110
	v_exp_f32_e32 v111, v111
	v_exp_f32_e32 v100, v100
	v_exp_f32_e32 v101, v101
	v_exp_f32_e32 v102, v102
	v_exp_f32_e32 v103, v103
	v_pk_mul_f32 v[88:89], v[92:93], v[88:89]
	v_pk_mul_f32 v[90:91], v[94:95], v[90:91]
	v_pk_mul_f32 v[80:81], v[84:85], v[80:81]
	v_pk_mul_f32 v[82:83], v[86:87], v[82:83]
	s_waitcnt lgkmcnt(2)
	v_cvt_pk_bf16_f32 v166, v166, v167
	v_cvt_pk_bf16_f32 v167, v168, v169
	v_cvt_pk_bf16_f32 v168, v170, v171
	v_cvt_pk_bf16_f32 v169, v172, v173
	global_store_dwordx4 v244, v[166:169], s[4:5] nt
	v_pk_fma_f32 v[108:109], v[108:109], v[162:163], v[162:163]
	v_pk_fma_f32 v[110:111], v[110:111], v[164:165], v[164:165]
	v_pk_fma_f32 v[100:101], v[100:101], v[162:163], v[162:163]
	v_pk_fma_f32 v[102:103], v[102:103], v[164:165], v[164:165]
	v_rcp_f32_e32 v108, v108
	v_rcp_f32_e32 v109, v109
	v_rcp_f32_e32 v110, v110
	v_rcp_f32_e32 v111, v111
	v_rcp_f32_e32 v100, v100
	v_rcp_f32_e32 v101, v101
	v_rcp_f32_e32 v102, v102
	v_rcp_f32_e32 v103, v103
	v_pk_mul_f32 v[104:105], v[104:105], v[108:109]
	v_pk_mul_f32 v[106:107], v[106:107], v[110:111]
	v_pk_mul_f32 v[96:97], v[96:97], v[100:101]
	v_pk_mul_f32 v[98:99], v[98:99], v[102:103]
	ds_write2_b32 v242, v104, v96 offset1:16
	ds_write2_b32 v242, v105, v97 offset0:36 offset1:52
	ds_write2_b32 v242, v106, v98 offset0:72 offset1:88
	ds_write2_b32 v242, v107, v99 offset0:108 offset1:124
	ds_read_b128 v[190:193], v241
	ds_read_b128 v[194:197], v241 offset:16
	ds_read_b128 v[154:157], v142 offset:192
	ds_read_b128 v[162:165], v142 offset:20672
	s_waitcnt lgkmcnt(8)
; __device__ __forceinline__ unsigned pack2(float lo, float hi) { unsigned r; asm volatile("v_cvt_pk_bf16_f32 %0, %1, %2" : "=v"(r) : "v"(lo), "v"(hi)); return r; }
; template <int EPI>
; __device__ __forceinline__ void gemm_phase(const GemmDesc d, u16* shm, unsigned sx, unsigned srank, unsigned snloc) {
;     ...
;         for (int ai = 0; ai < 2; ++ai)
; #pragma unroll
;           for (int m = 0; m < 4; ++m) {
;             const f32x4 r4 = *(const f32x4*)&lr[ai * 128 + wr2 * 64 + m * 16 + fq2 * 4];
;             const f32x4 rc4 = r4 * (-1.4426950408889634f), rr4 = r4 * r4;
; #pragma unroll
;             for (int n = 0; n < 2; ++n)
; #pragma unroll
;               for (int jp = 0; jp < 4; jp += 2) {
;                 const f32x2 a = {acc[ai][0][m][n][jp], acc[ai][0][m][n][jp + 1]}, b = {acc[ai][1][m][n][jp], acc[ai][1][m][n][jp + 1]};
;                 const f32x2 rc = {rc4[jp], rc4[jp + 1]}, rr = {rr4[jp], rr4[jp + 1]};
;                 const f32x2 tl = a * rc;
;                 f32x2 dd = {__builtin_amdgcn_exp2f(tl[0]), __builtin_amdgcn_exp2f(tl[1])};
;                 dd = dd + 1.0f;
;                 const f32x2 s = {__builtin_amdgcn_rcpf(dd[0]), __builtin_amdgcn_rcpf(dd[1])};
;                 const f32x2 o = (a * b) * (rr * s);
;                 stg[(fq2 * 4 + jp) * 36 + n * 16 + fr2] = o[0];
;                 stg[(fq2 * 4 + jp + 1) * 36 + n * 16 + fr2] = o[1];
;               }
;             {
;               const f32x4 v0 = *(const f32x4*)&stg[sw_row * 36 + sw_c8], v1 = *(const f32x4*)&stg[sw_row * 36 + sw_c8 + 4];
;               u32x4 w = {pack2(v0[0], v0[1]), pack2(v0[2], v0[3]), pack2(v1[0], v1[1]), pack2(v1[2], v1[3])};
;               __builtin_nontemporal_store(w, (u32x4*)(sw_base + (size_t)ai * (44 * 8192) + m * 1024));
;             }
	v_pk_mul_f32 v[92:93], v[92:93], v[150:151]
	v_pk_mul_f32 v[94:95], v[94:95], v[152:153]
	v_pk_mul_f32 v[84:85], v[84:85], v[150:151]
	v_pk_mul_f32 v[86:87], v[86:87], v[152:153]
	v_exp_f32_e32 v92, v92
	v_exp_f32_e32 v93, v93
	v_exp_f32_e32 v94, v94
	v_exp_f32_e32 v95, v95
	v_exp_f32_e32 v84, v84
	v_exp_f32_e32 v85, v85
	v_exp_f32_e32 v86, v86
	v_exp_f32_e32 v87, v87
	v_pk_mul_f32 v[72:73], v[76:77], v[72:73]
	v_pk_mul_f32 v[74:75], v[78:79], v[74:75]
	v_pk_mul_f32 v[64:65], v[68:69], v[64:65]
	v_pk_mul_f32 v[66:67], v[70:71], v[66:67]
	s_waitcnt lgkmcnt(2)
	v_cvt_pk_bf16_f32 v190, v190, v191
	v_cvt_pk_bf16_f32 v191, v192, v193
	v_cvt_pk_bf16_f32 v192, v194, v195
	v_cvt_pk_bf16_f32 v193, v196, v197
	global_store_dwordx4 v244, v[190:193], s[4:5] offset:2048 nt
	v_pk_fma_f32 v[92:93], v[92:93], v[158:159], v[158:159]
	v_pk_fma_f32 v[94:95], v[94:95], v[160:161], v[160:161]
	v_pk_fma_f32 v[84:85], v[84:85], v[158:159], v[158:159]
	v_pk_fma_f32 v[86:87], v[86:87], v[160:161], v[160:161]
	v_rcp_f32_e32 v92, v92
	v_rcp_f32_e32 v93, v93
	v_rcp_f32_e32 v94, v94
	v_rcp_f32_e32 v95, v95
	v_rcp_f32_e32 v84, v84
	v_rcp_f32_e32 v85, v85
	v_rcp_f32_e32 v86, v86
	v_rcp_f32_e32 v87, v87
	v_pk_mul_f32 v[88:89], v[88:89], v[92:93]
	v_pk_mul_f32 v[90:91], v[90:91], v[94:95]
	v_pk_mul_f32 v[80:81], v[80:81], v[84:85]
	v_pk_mul_f32 v[82:83], v[82:83], v[86:87]
	ds_write2_b32 v242, v88, v80 offset1:16
	ds_write2_b32 v242, v89, v81 offset0:36 offset1:52
	ds_write2_b32 v242, v90, v82 offset0:72 offset1:88
	ds_write2_b32 v242, v91, v83 offset0:108 offset1:124
	ds_read_b128 v[166:169], v241
	ds_read_b128 v[170:173], v241 offset:16
	ds_read_b128 v[150:153], v142 offset:512
	ds_read_b128 v[158:161], v142 offset:20992
	s_waitcnt lgkmcnt(8)
	v_pk_mul_f32 v[76:77], v[76:77], v[154:155]
	v_pk_mul_f32 v[78:79], v[78:79], v[156:157]
	v_pk_mul_f32 v[68:69], v[68:69], v[154:155]
	v_pk_mul_f32 v[70:71], v[70:71], v[156:157]
	v_exp_f32_e32 v76, v76
	v_exp_f32_e32 v77, v77
	v_exp_f32_e32 v78, v78
	v_exp_f32_e32 v79, v79
	v_exp_f32_e32 v68, v68
	v_exp_f32_e32 v69, v69
	v_exp_f32_e32 v70, v70
	v_exp_f32_e32 v71, v71
	v_pk_mul_f32 v[56:57], v[60:61], v[56:57]
	v_pk_mul_f32 v[58:59], v[62:63], v[58:59]
	v_pk_mul_f32 v[48:49], v[52:53], v[48:49]
	v_pk_mul_f32 v[50:51], v[54:55], v[50:51]
	s_waitcnt lgkmcnt(2)
	v_cvt_pk_bf16_f32 v166, v166, v167
	v_cvt_pk_bf16_f32 v167, v168, v169
	v_cvt_pk_bf16_f32 v168, v170, v171
	v_cvt_pk_bf16_f32 v169, v172, v173
	global_store_dwordx4 v244, v[166:169], s[40:41] nt
	v_pk_fma_f32 v[76:77], v[76:77], v[162:163], v[162:163]
	v_pk_fma_f32 v[78:79], v[78:79], v[164:165], v[164:165]
	v_pk_fma_f32 v[68:69], v[68:69], v[162:163], v[162:163]
	v_pk_fma_f32 v[70:71], v[70:71], v[164:165], v[164:165]
	v_rcp_f32_e32 v76, v76
	v_rcp_f32_e32 v77, v77
	v_rcp_f32_e32 v78, v78
	v_rcp_f32_e32 v79, v79
	v_rcp_f32_e32 v68, v68
	v_rcp_f32_e32 v69, v69
	v_rcp_f32_e32 v70, v70
	v_rcp_f32_e32 v71, v71
	v_pk_mul_f32 v[72:73], v[72:73], v[76:77]
	v_pk_mul_f32 v[74:75], v[74:75], v[78:79]
	v_pk_mul_f32 v[64:65], v[64:65], v[68:69]
	v_pk_mul_f32 v[66:67], v[66:67], v[70:71]
	ds_write2_b32 v242, v72, v64 offset1:16
	ds_write2_b32 v242, v73, v65 offset0:36 offset1:52
	ds_write2_b32 v242, v74, v66 offset0:72 offset1:88
	ds_write2_b32 v242, v75, v67 offset0:108 offset1:124
	ds_read_b128 v[190:193], v241
	ds_read_b128 v[194:197], v241 offset:16
	ds_read_b128 v[154:157], v142 offset:576
	ds_read_b128 v[162:165], v142 offset:21056
	s_waitcnt lgkmcnt(8)
	v_pk_mul_f32 v[60:61], v[60:61], v[150:151]
	v_pk_mul_f32 v[62:63], v[62:63], v[152:153]
	v_pk_mul_f32 v[52:53], v[52:53], v[150:151]
	v_pk_mul_f32 v[54:55], v[54:55], v[152:153]
	v_exp_f32_e32 v60, v60
	v_exp_f32_e32 v61, v61
	v_exp_f32_e32 v62, v62
	v_exp_f32_e32 v63, v63
	v_exp_f32_e32 v52, v52
	v_exp_f32_e32 v53, v53
	v_exp_f32_e32 v54, v54
	v_exp_f32_e32 v55, v55
	v_pk_mul_f32 v[40:41], v[44:45], v[40:41]
	v_pk_mul_f32 v[42:43], v[46:47], v[42:43]
	v_pk_mul_f32 v[32:33], v[36:37], v[32:33]
	v_pk_mul_f32 v[34:35], v[38:39], v[34:35]
	s_waitcnt lgkmcnt(2)
	v_cvt_pk_bf16_f32 v190, v190, v191
	v_cvt_pk_bf16_f32 v191, v192, v193
	v_cvt_pk_bf16_f32 v192, v194, v195
	v_cvt_pk_bf16_f32 v193, v196, v197
	global_store_dwordx4 v244, v[190:193], s[40:41] offset:2048 nt
	v_pk_fma_f32 v[60:61], v[60:61], v[158:159], v[158:159]
	v_pk_fma_f32 v[62:63], v[62:63], v[160:161], v[160:161]
	v_pk_fma_f32 v[52:53], v[52:53], v[158:159], v[158:159]
	v_pk_fma_f32 v[54:55], v[54:55], v[160:161], v[160:161]
	v_rcp_f32_e32 v60, v60
	v_rcp_f32_e32 v61, v61
	v_rcp_f32_e32 v62, v62
	v_rcp_f32_e32 v63, v63
	v_rcp_f32_e32 v52, v52
	v_rcp_f32_e32 v53, v53
	v_rcp_f32_e32 v54, v54
	v_rcp_f32_e32 v55, v55
	v_pk_mul_f32 v[56:57], v[56:57], v[60:61]
	v_pk_mul_f32 v[58:59], v[58:59], v[62:63]
	v_pk_mul_f32 v[48:49], v[48:49], v[52:53]
	v_pk_mul_f32 v[50:51], v[50:51], v[54:55]
	ds_write2_b32 v242, v56, v48 offset1:16
	ds_write2_b32 v242, v57, v49 offset0:36 offset1:52
	ds_write2_b32 v242, v58, v50 offset0:72 offset1:88
	ds_write2_b32 v242, v59, v51 offset0:108 offset1:124
	ds_read_b128 v[166:169], v241
	ds_read_b128 v[170:173], v241 offset:16
	ds_read_b128 v[150:153], v142 offset:640
	ds_read_b128 v[158:161], v142 offset:21120
	s_waitcnt lgkmcnt(8)
; __device__ __forceinline__ unsigned pack2(float lo, float hi) { unsigned r; asm volatile("v_cvt_pk_bf16_f32 %0, %1, %2" : "=v"(r) : "v"(lo), "v"(hi)); return r; }
; template <int EPI>
; __device__ __forceinline__ void gemm_phase(const GemmDesc d, u16* shm, unsigned sx, unsigned srank, unsigned snloc) {
;     ...
; #pragma unroll
;         for (int ai = 0; ai < 2; ++ai)
; #pragma unroll
;           for (int m = 0; m < 4; ++m) {
;             const f32x4 r4 = *(const f32x4*)&lr[ai * 128 + wr2 * 64 + m * 16 + fq2 * 4];
;             const f32x4 rc4 = r4 * (-1.4426950408889634f), rr4 = r4 * r4;
; #pragma unroll
;             for (int n = 0; n < 2; ++n)
; #pragma unroll
;               for (int jp = 0; jp < 4; jp += 2) {
;                 const f32x2 a = {acc[ai][0][m][n][jp], acc[ai][0][m][n][jp + 1]}, b = {acc[ai][1][m][n][jp], acc[ai][1][m][n][jp + 1]};
;                 const f32x2 rc = {rc4[jp], rc4[jp + 1]}, rr = {rr4[jp], rr4[jp + 1]};
;                 const f32x2 tl = a * rc;
;                 f32x2 dd = {__builtin_amdgcn_exp2f(tl[0]), __builtin_amdgcn_exp2f(tl[1])};
;                 dd = dd + 1.0f;
;                 const f32x2 s = {__builtin_amdgcn_rcpf(dd[0]), __builtin_amdgcn_rcpf(dd[1])};
;                 const f32x2 o = (a * b) * (rr * s);
;                 stg[(fq2 * 4 + jp) * 36 + n * 16 + fr2] = o[0];
;                 stg[(fq2 * 4 + jp + 1) * 36 + n * 16 + fr2] = o[1];
;               }
;             {
;               const f32x4 v0 = *(const f32x4*)&stg[sw_row * 36 + sw_c8], v1 = *(const f32x4*)&stg[sw_row * 36 + sw_c8 + 4];
;               u32x4 w = {pack2(v0[0], v0[1]), pack2(v0[2], v0[3]), pack2(v1[0], v1[1]), pack2(v1[2], v1[3])};
;               __builtin_nontemporal_store(w, (u32x4*)(sw_base + (size_t)ai * (44 * 8192) + m * 1024));
;             }
;           }
;     ...
;       if constexpr (NEED_R) {
;         if (has_next && t2 < 256) lds_r[((it + 1) & 1) * 256 + t2] = R_ZERO(pnn, t2) ? 0.f : rsqrtf(ssn * (1.0f / DM) + EPS);
;       }
	v_pk_mul_f32 v[44:45], v[44:45], v[154:155]
	v_pk_mul_f32 v[46:47], v[46:47], v[156:157]
	v_pk_mul_f32 v[36:37], v[36:37], v[154:155]
	v_pk_mul_f32 v[38:39], v[38:39], v[156:157]
	v_exp_f32_e32 v44, v44
	v_exp_f32_e32 v45, v45
	v_exp_f32_e32 v46, v46
	v_exp_f32_e32 v47, v47
	v_exp_f32_e32 v36, v36
	v_exp_f32_e32 v37, v37
	v_exp_f32_e32 v38, v38
	v_exp_f32_e32 v39, v39
	v_pk_mul_f32 v[24:25], v[28:29], v[24:25]
	v_pk_mul_f32 v[26:27], v[30:31], v[26:27]
	v_pk_mul_f32 v[16:17], v[20:21], v[16:17]
	v_pk_mul_f32 v[18:19], v[22:23], v[18:19]
	s_waitcnt lgkmcnt(2)
	v_cvt_pk_bf16_f32 v166, v166, v167
	v_cvt_pk_bf16_f32 v167, v168, v169
	v_cvt_pk_bf16_f32 v168, v170, v171
	v_cvt_pk_bf16_f32 v169, v172, v173
	global_store_dwordx4 v244, v[166:169], s[22:23] nt
	v_pk_fma_f32 v[44:45], v[44:45], v[162:163], v[162:163]
	v_pk_fma_f32 v[46:47], v[46:47], v[164:165], v[164:165]
	v_pk_fma_f32 v[36:37], v[36:37], v[162:163], v[162:163]
	v_pk_fma_f32 v[38:39], v[38:39], v[164:165], v[164:165]
	v_rcp_f32_e32 v44, v44
	v_rcp_f32_e32 v45, v45
	v_rcp_f32_e32 v46, v46
	v_rcp_f32_e32 v47, v47
	v_rcp_f32_e32 v36, v36
	v_rcp_f32_e32 v37, v37
	v_rcp_f32_e32 v38, v38
	v_rcp_f32_e32 v39, v39
	v_pk_mul_f32 v[40:41], v[40:41], v[44:45]
	v_pk_mul_f32 v[42:43], v[42:43], v[46:47]
	v_pk_mul_f32 v[32:33], v[32:33], v[36:37]
	v_pk_mul_f32 v[34:35], v[34:35], v[38:39]
	ds_write2_b32 v242, v40, v32 offset1:16
	ds_write2_b32 v242, v41, v33 offset0:36 offset1:52
	ds_write2_b32 v242, v42, v34 offset0:72 offset1:88
	ds_write2_b32 v242, v43, v35 offset0:108 offset1:124
	ds_read_b128 v[190:193], v241
	ds_read_b128 v[194:197], v241 offset:16
	ds_read_b128 v[154:157], v142 offset:704
	ds_read_b128 v[162:165], v142 offset:21184
	s_waitcnt lgkmcnt(8)
	v_pk_mul_f32 v[28:29], v[28:29], v[150:151]
	v_pk_mul_f32 v[30:31], v[30:31], v[152:153]
	v_pk_mul_f32 v[20:21], v[20:21], v[150:151]
	v_pk_mul_f32 v[22:23], v[22:23], v[152:153]
	v_exp_f32_e32 v28, v28
	v_exp_f32_e32 v29, v29
	v_exp_f32_e32 v30, v30
	v_exp_f32_e32 v31, v31
	v_exp_f32_e32 v20, v20
	v_exp_f32_e32 v21, v21
	v_exp_f32_e32 v22, v22
	v_exp_f32_e32 v23, v23
	v_pk_mul_f32 v[8:9], v[12:13], v[8:9]
	v_pk_mul_f32 v[10:11], v[14:15], v[10:11]
	v_pk_mul_f32 v[0:1], v[4:5], v[0:1]
	v_pk_mul_f32 v[2:3], v[6:7], v[2:3]
	s_waitcnt lgkmcnt(2)
	v_cvt_pk_bf16_f32 v190, v190, v191
	v_cvt_pk_bf16_f32 v191, v192, v193
	v_cvt_pk_bf16_f32 v192, v194, v195
	v_cvt_pk_bf16_f32 v193, v196, v197
	global_store_dwordx4 v244, v[190:193], s[22:23] offset:2048 nt
	v_pk_fma_f32 v[28:29], v[28:29], v[158:159], v[158:159]
	v_pk_fma_f32 v[30:31], v[30:31], v[160:161], v[160:161]
	v_pk_fma_f32 v[20:21], v[20:21], v[158:159], v[158:159]
	v_pk_fma_f32 v[22:23], v[22:23], v[160:161], v[160:161]
	v_rcp_f32_e32 v28, v28
	v_rcp_f32_e32 v29, v29
	v_rcp_f32_e32 v30, v30
	v_rcp_f32_e32 v31, v31
	v_rcp_f32_e32 v20, v20
	v_rcp_f32_e32 v21, v21
	v_rcp_f32_e32 v22, v22
	v_rcp_f32_e32 v23, v23
	v_pk_mul_f32 v[24:25], v[24:25], v[28:29]
	v_pk_mul_f32 v[26:27], v[26:27], v[30:31]
	v_pk_mul_f32 v[16:17], v[16:17], v[20:21]
	v_pk_mul_f32 v[18:19], v[18:19], v[22:23]
	ds_write2_b32 v242, v24, v16 offset1:16
	ds_write2_b32 v242, v25, v17 offset0:36 offset1:52
	ds_write2_b32 v242, v26, v18 offset0:72 offset1:88
	ds_write2_b32 v242, v27, v19 offset0:108 offset1:124
	ds_read_b128 v[166:169], v241
	ds_read_b128 v[170:173], v241 offset:16
	s_waitcnt lgkmcnt(6)
	v_pk_mul_f32 v[12:13], v[12:13], v[154:155]
	v_pk_mul_f32 v[14:15], v[14:15], v[156:157]
	v_pk_mul_f32 v[4:5], v[4:5], v[154:155]
	v_pk_mul_f32 v[6:7], v[6:7], v[156:157]
	v_exp_f32_e32 v12, v12
	v_exp_f32_e32 v13, v13
	v_exp_f32_e32 v14, v14
	v_exp_f32_e32 v15, v15
	v_exp_f32_e32 v4, v4
	v_exp_f32_e32 v5, v5
	v_exp_f32_e32 v6, v6
	v_exp_f32_e32 v7, v7
	s_waitcnt lgkmcnt(0)
	v_cvt_pk_bf16_f32 v166, v166, v167
	v_cvt_pk_bf16_f32 v167, v168, v169
	v_cvt_pk_bf16_f32 v168, v170, v171
	v_cvt_pk_bf16_f32 v169, v172, v173
	global_store_dwordx4 v244, v[166:169], s[96:97] nt
	v_pk_fma_f32 v[12:13], v[12:13], v[162:163], v[162:163]
	v_pk_fma_f32 v[14:15], v[14:15], v[164:165], v[164:165]
	v_pk_fma_f32 v[4:5], v[4:5], v[162:163], v[162:163]
	v_pk_fma_f32 v[6:7], v[6:7], v[164:165], v[164:165]
	v_rcp_f32_e32 v12, v12
	v_rcp_f32_e32 v13, v13
	v_rcp_f32_e32 v14, v14
	v_rcp_f32_e32 v15, v15
	v_rcp_f32_e32 v4, v4
	v_rcp_f32_e32 v5, v5
	v_rcp_f32_e32 v6, v6
	v_rcp_f32_e32 v7, v7
	v_pk_mul_f32 v[8:9], v[8:9], v[12:13]
	v_pk_mul_f32 v[10:11], v[10:11], v[14:15]
	v_pk_mul_f32 v[0:1], v[0:1], v[4:5]
	v_pk_mul_f32 v[2:3], v[2:3], v[6:7]
	ds_write2_b32 v242, v8, v0 offset1:16
	ds_write2_b32 v242, v9, v1 offset0:36 offset1:52
	ds_write2_b32 v242, v10, v2 offset0:72 offset1:88
	ds_write2_b32 v242, v11, v3 offset0:108 offset1:124
	ds_read_b128 v[190:193], v241
	ds_read_b128 v[194:197], v241 offset:16
	s_waitcnt lgkmcnt(0)
	v_cvt_pk_bf16_f32 v190, v190, v191
	v_cvt_pk_bf16_f32 v191, v192, v193
	v_cvt_pk_bf16_f32 v192, v194, v195
	v_cvt_pk_bf16_f32 v193, v196, v197
	global_store_dwordx4 v244, v[190:193], s[96:97] offset:2048 nt
	s_and_saveexec_b64 s[4:5], s[34:35]
	s_cbranch_execz .LBB0_1454
	v_cmp_gt_f32_e32 vcc, s31, v140
	v_mul_f32_e32 v0, 0x4b800000, v140
	s_xor_b32 s0, s18, 0x100
	v_cndmask_b32_e32 v0, v140, v0, vcc
	v_rsq_f32_e32 v0, v0
	s_lshl_b32 s0, s0, 2
	s_add_i32 s0, s0, 0
	v_mul_f32_e32 v1, 0x45800000, v0
	v_cndmask_b32_e32 v0, v0, v1, vcc
	v_lshl_add_u32 v1, v139, 2, s0
	v_add_u32_e32 v1, 0x20000, v1
	v_mul_f32_e32 v0, s86, v0
	ds_write_b32 v1, v0
	ds_write_b32 v1, v140 offset:20480
